# ML gate cumsum: 64-step single-thread LDS chain replaced by a DPP wave scan (both chunk_local and chunk_out)
# baseline (speedup 1.0000x reference)
; __device__ __forceinline__ void ml_gates(LAS unsigned char* lds, const bf16_t* P, int c, int h, const float* bif, int tid) {
;     ...
;   __syncthreads();
;   if (tid == 0) { float run = 0.f; for (int t = 0; t < 64; ++t) { run += GM(0)[t]; GM(0)[t] = run; } }
;   __syncthreads();
.LBB0_141:
	s_or_b64 exec, exec, s[30:31]
	s_waitcnt lgkmcnt(0)
	s_barrier
	s_and_saveexec_b64 s[36:37], s[34:35]
	s_cbranch_execz .LBB0_143
	s_mov_b64 exec, -1
	v_mbcnt_lo_u32_b32 v4, -1, 0
	v_mbcnt_hi_u32_b32 v4, -1, v4
	v_lshl_add_u32 v6, v4, 2, s28
	ds_read_b32 v4, v6
	s_waitcnt lgkmcnt(0)
	s_nop 1
	v_add_f32_dpp v4, v4, v4 row_shr:1 row_mask:0xf bank_mask:0xf bound_ctrl:1
	s_nop 1
	v_add_f32_dpp v4, v4, v4 row_shr:2 row_mask:0xf bank_mask:0xf bound_ctrl:1
	s_nop 1
	v_add_f32_dpp v4, v4, v4 row_shr:4 row_mask:0xf bank_mask:0xf bound_ctrl:1
	s_nop 1
	v_add_f32_dpp v4, v4, v4 row_shr:8 row_mask:0xf bank_mask:0xf bound_ctrl:1
	s_nop 1
	v_mov_b32_e32 v5, 0
	s_nop 1
	v_mov_b32_dpp v5, v4 row_bcast:15 row_mask:0xa bank_mask:0xf
	s_nop 1
	v_add_f32_e32 v4, v4, v5
	v_mov_b32_e32 v5, 0
	s_nop 1
	v_mov_b32_dpp v5, v4 row_bcast:31 row_mask:0xc bank_mask:0xf
	s_nop 1
	v_add_f32_e32 v4, v4, v5
	ds_write_b32 v6, v4

; __device__ __forceinline__ void ml_gates(LAS unsigned char* lds, const bf16_t* P, int c, int h, const float* bif, int tid) {
;     ...
;   __syncthreads();
;   if (tid == 0) { float run = 0.f; for (int t = 0; t < 64; ++t) { run += GM(0)[t]; GM(0)[t] = run; } }
;   __syncthreads();
.LBB0_334:
	s_or_b64 exec, exec, s[20:21]
	s_waitcnt lgkmcnt(0)
	s_barrier
	s_and_saveexec_b64 s[10:11], s[4:5]
	s_cbranch_execz .LBB0_336
	s_mov_b64 exec, -1
	v_mbcnt_lo_u32_b32 v2, -1, 0
	v_mbcnt_hi_u32_b32 v2, -1, v2
	v_lshl_add_u32 v4, v2, 2, s22
	ds_read_b32 v2, v4
	s_waitcnt lgkmcnt(0)
	s_nop 1
	v_add_f32_dpp v2, v2, v2 row_shr:1 row_mask:0xf bank_mask:0xf bound_ctrl:1
	s_nop 1
	v_add_f32_dpp v2, v2, v2 row_shr:2 row_mask:0xf bank_mask:0xf bound_ctrl:1
	s_nop 1
	v_add_f32_dpp v2, v2, v2 row_shr:4 row_mask:0xf bank_mask:0xf bound_ctrl:1
	s_nop 1
	v_add_f32_dpp v2, v2, v2 row_shr:8 row_mask:0xf bank_mask:0xf bound_ctrl:1
	s_nop 1
	v_mov_b32_e32 v3, 0
	s_nop 1
	v_mov_b32_dpp v3, v2 row_bcast:15 row_mask:0xa bank_mask:0xf
	s_nop 1
	v_add_f32_e32 v2, v2, v3
	v_mov_b32_e32 v3, 0
	s_nop 1
	v_mov_b32_dpp v3, v2 row_bcast:31 row_mask:0xc bank_mask:0xf
	s_nop 1
	v_add_f32_e32 v2, v2, v3
	ds_write_b32 v4, v2
